# fused P9 software-pipelined: next row's 24 loads issued before this row's 8 stores (X/T register roles swap per row), so no wait has a store older than the load it needs
# speedup vs baseline: 1.0047x; 1.0047x over previous
; #define PHASE_IDS() int tid_p = threadIdx.x; asm volatile("" : "+v"(tid_p)); const int lane = tid_p & 63; const int wave_p = __builtin_amdgcn_readfirstlane(tid_p >> 6); \
;     const int gw = vcu * NWAVES + wave_p, NGW = G * NWAVES; const size_t gt = (size_t)bx * NTHREADS + tid_p, NGT = (size_t)G * NTHREADS; (void)lane; (void)gw; (void)NGW; (void)gt; (void)NGT
; __global__ void __launch_bounds__(NTHREADS, 2) fwd_megakernel(Args args) {
;     ...
;     for (int m = gw; m < MTOK; m += NGW) {
;         float* row = HF + (size_t)m * DM; const float* xr = x + (size_t)m * DM; const bf16* mr = MIXB + (size_t)m * DM; f32x4 v[8]; float s = 0.f;
; #pragma unroll
;         for (int j = 0; j < 8; ++j) { const int c = 4 * (lane + 64 * j); const f32x4 xv = __builtin_nontemporal_load((const f32x4*)(xr + c)); const v2u mv = *(const v2u*)(mr + c);
;     ...
;     { PHASE_IDS();
;     for (int m = gw; m < MTOK; m += NGW) {
;         const float* row = HF + (size_t)m * DM; const bf16* mr = MIXB + (size_t)m * DM; f32x4 v[8]; float s = 0.f;
; #pragma unroll
;         for (int j = 0; j < 8; ++j) { const int c = 4 * (lane + 64 * j); const f32x4 hv = *(const f32x4*)(row + c); const v2u mv = *(const v2u*)(mr + c);
.LBB0_609:
	s_or_b64 exec, exec, s[2:3]
	s_waitcnt lgkmcnt(0)
	s_barrier
	s_nop 0
	v_readfirstlane_b32 s0, v178
	s_ashr_i32 s0, s0, 6
	s_add_i32 s11, s0, s89
	s_cmpk_gt_i32 s11, 0x7fff
	s_cbranch_scc1 .LBB0_612
	s_mov_b32 s16, s11
	v_readlane_b32 s18, v244, 16
	v_readlane_b32 s19, v244, 17
	v_readlane_b32 s20, v244, 18
	v_readlane_b32 s21, v244, 19
	v_readlane_b32 s22, v244, 20
	v_readlane_b32 s23, v244, 21
	v_mbcnt_lo_u32_b32 v97, -1, 0
	v_mbcnt_hi_u32_b32 v97, -1, v97
	v_lshlrev_b32_e32 v106, 4, v97
	v_add_u32_e32 v107, 0x1000, v106
	v_lshlrev_b32_e32 v108, 3, v97
	v_xor_b32_e32 v109, 1, v97
	v_lshlrev_b32_e32 v109, 2, v109
	v_xor_b32_e32 v110, 2, v97
	v_lshlrev_b32_e32 v110, 2, v110
	v_xor_b32_e32 v111, 4, v97
	v_lshlrev_b32_e32 v111, 2, v111
	v_xor_b32_e32 v240, 8, v97
	v_lshlrev_b32_e32 v240, 2, v240
	v_xor_b32_e32 v241, 16, v97
	v_lshlrev_b32_e32 v241, 2, v241
	v_xor_b32_e32 v242, 32, v97
	v_lshlrev_b32_e32 v242, 2, v242
	v_mov_b32_e32 v105, 0x3727c5ac
	v_mov_b32_e32 v104, 0x260
	s_mov_b32 s10, 0x3f9837f0
	s_mov_b32 s17, 0xf800000
	s_lshl_b32 s0, s16, 13
	s_add_u32 s2, s38, s0
	s_addc_u32 s3, s39, 0
	s_add_u32 s4, s18, s0
	s_addc_u32 s5, s19, 0
	s_lshl_b32 s0, s16, 12
	s_add_u32 s6, s40, s0
	s_addc_u32 s7, s41, 0
	s_add_u32 s8, s6, 0x7c00000
	s_addc_u32 s9, s7, 0
	s_add_u32 s6, s6, 0xfc00000
	s_addc_u32 s7, s7, 0
	s_lshl_b32 s12, s28, 13
	s_mov_b32 s13, 0
	s_lshl_b32 s14, s28, 12
	s_mov_b32 s15, 0
	global_load_dwordx4 v[0:3], v106, s[4:5] nt
	global_load_dwordx4 v[4:7], v106, s[4:5] offset:1024 nt
	global_load_dwordx4 v[8:11], v106, s[4:5] offset:2048 nt
	global_load_dwordx4 v[12:15], v106, s[4:5] offset:3072 nt
	global_load_dwordx4 v[16:19], v107, s[4:5] nt
	global_load_dwordx4 v[20:23], v107, s[4:5] offset:1024 nt
	global_load_dwordx4 v[24:27], v107, s[4:5] offset:2048 nt
	global_load_dwordx4 v[28:31], v107, s[4:5] offset:3072 nt
	global_load_dwordx2 v[32:33], v108, s[6:7]
	global_load_dwordx2 v[34:35], v108, s[6:7] offset:512
	global_load_dwordx2 v[36:37], v108, s[6:7] offset:1024
	global_load_dwordx2 v[38:39], v108, s[6:7] offset:1536
	global_load_dwordx2 v[40:41], v108, s[6:7] offset:2048
	global_load_dwordx2 v[42:43], v108, s[6:7] offset:2560
	global_load_dwordx2 v[44:45], v108, s[6:7] offset:3072
	global_load_dwordx2 v[46:47], v108, s[6:7] offset:3584
	global_load_dwordx2 v[48:49], v108, s[8:9]
	global_load_dwordx2 v[50:51], v108, s[8:9] offset:512
	global_load_dwordx2 v[52:53], v108, s[8:9] offset:1024
	global_load_dwordx2 v[54:55], v108, s[8:9] offset:1536
	global_load_dwordx2 v[56:57], v108, s[8:9] offset:2048
	global_load_dwordx2 v[58:59], v108, s[8:9] offset:2560
	global_load_dwordx2 v[60:61], v108, s[8:9] offset:3072
	global_load_dwordx2 v[62:63], v108, s[8:9] offset:3584
	s_add_u32 s4, s4, s12
	s_addc_u32 s5, s5, s13
	s_add_u32 s6, s6, s14
	s_addc_u32 s7, s7, s15
	s_add_u32 s8, s8, s14
	s_addc_u32 s9, s9, s15
	global_load_dwordx4 v[112:115], v106, s[20:21]
	global_load_dwordx4 v[116:119], v106, s[20:21] offset:1024
	global_load_dwordx4 v[120:123], v106, s[20:21] offset:2048
	global_load_dwordx4 v[124:127], v106, s[20:21] offset:3072
	global_load_dwordx4 v[128:131], v107, s[20:21]
	global_load_dwordx4 v[132:135], v107, s[20:21] offset:1024
	global_load_dwordx4 v[136:139], v107, s[20:21] offset:2048
	global_load_dwordx4 v[140:143], v107, s[20:21] offset:3072
	global_load_dwordx4 v[144:147], v106, s[22:23]
	global_load_dwordx4 v[148:151], v106, s[22:23] offset:1024
	global_load_dwordx4 v[152:155], v106, s[22:23] offset:2048
	global_load_dwordx4 v[156:159], v106, s[22:23] offset:3072
	global_load_dwordx4 v[160:163], v107, s[22:23]
	global_load_dwordx4 v[164:167], v107, s[22:23] offset:1024
	global_load_dwordx4 v[168:171], v107, s[22:23] offset:2048
	global_load_dwordx4 v[172:175], v107, s[22:23] offset:3072
	global_load_dwordx4 v[176:179], v106, s[48:49]
	global_load_dwordx4 v[180:183], v106, s[48:49] offset:1024
	global_load_dwordx4 v[184:187], v106, s[48:49] offset:2048
	global_load_dwordx4 v[188:191], v106, s[48:49] offset:3072
	global_load_dwordx4 v[192:195], v107, s[48:49]
	global_load_dwordx4 v[196:199], v107, s[48:49] offset:1024
	global_load_dwordx4 v[200:203], v107, s[48:49] offset:2048
	global_load_dwordx4 v[204:207], v107, s[48:49] offset:3072
	global_load_dwordx4 v[208:211], v106, s[50:51]
	global_load_dwordx4 v[212:215], v106, s[50:51] offset:1024
	global_load_dwordx4 v[216:219], v106, s[50:51] offset:2048
	global_load_dwordx4 v[220:223], v106, s[50:51] offset:3072
	global_load_dwordx4 v[224:227], v107, s[50:51]
	global_load_dwordx4 v[228:231], v107, s[50:51] offset:1024
	global_load_dwordx4 v[232:235], v107, s[50:51] offset:2048
	global_load_dwordx4 v[236:239], v107, s[50:51] offset:3072
	s_waitcnt vmcnt(0)
; __global__ void __launch_bounds__(NTHREADS, 2) fwd_megakernel(Args args) {
;     ...
;         float* row = HF + (size_t)m * DM; const float* xr = x + (size_t)m * DM; const bf16* mr = MIXB + (size_t)m * DM; f32x4 v[8]; float s = 0.f;
; #pragma unroll
;         for (int j = 0; j < 8; ++j) { const int c = 4 * (lane + 64 * j); const f32x4 xv = __builtin_nontemporal_load((const f32x4*)(xr + c)); const v2u mv = *(const v2u*)(mr + c);
;             v[j] = xv * ALPHA + (f32x4){bflo(mv.x), bfhi(mv.x), bflo(mv.y), bfhi(mv.y)}; s += (v[j][0] + v[j][1]) + (v[j][2] + v[j][3]); }
;         const float mean = wave_sum(s) * (1.f / DM); float s2 = 0.f;
; #pragma unroll
;         for (int j = 0; j < 8; ++j) { v[j] = v[j] - mean; s2 += (v[j][0] * v[j][0] + v[j][1] * v[j][1]) + (v[j][2] * v[j][2] + v[j][3] * v[j][3]); }
.Lp9r_loop:
	s_waitcnt vmcnt(16)
	v_lshlrev_b32_e32 v64, 16, v32
	v_and_b32_e32 v65, 0xffff0000, v32
	v_lshlrev_b32_e32 v66, 16, v33
	v_and_b32_e32 v67, 0xffff0000, v33
	v_lshlrev_b32_e32 v68, 16, v34
	v_and_b32_e32 v69, 0xffff0000, v34
	v_lshlrev_b32_e32 v70, 16, v35
	v_and_b32_e32 v71, 0xffff0000, v35
	v_lshlrev_b32_e32 v72, 16, v36
	v_and_b32_e32 v73, 0xffff0000, v36
	v_lshlrev_b32_e32 v74, 16, v37
	v_and_b32_e32 v75, 0xffff0000, v37
	v_lshlrev_b32_e32 v76, 16, v38
	v_and_b32_e32 v77, 0xffff0000, v38
	v_lshlrev_b32_e32 v78, 16, v39
	v_and_b32_e32 v79, 0xffff0000, v39
	v_lshlrev_b32_e32 v80, 16, v40
	v_and_b32_e32 v81, 0xffff0000, v40
	v_lshlrev_b32_e32 v82, 16, v41
	v_and_b32_e32 v83, 0xffff0000, v41
	v_lshlrev_b32_e32 v84, 16, v42
	v_and_b32_e32 v85, 0xffff0000, v42
	v_lshlrev_b32_e32 v86, 16, v43
	v_and_b32_e32 v87, 0xffff0000, v43
	v_lshlrev_b32_e32 v88, 16, v44
	v_and_b32_e32 v89, 0xffff0000, v44
	v_lshlrev_b32_e32 v90, 16, v45
	v_and_b32_e32 v91, 0xffff0000, v45
	v_lshlrev_b32_e32 v92, 16, v46
	v_and_b32_e32 v93, 0xffff0000, v46
	v_lshlrev_b32_e32 v94, 16, v47
	v_and_b32_e32 v95, 0xffff0000, v47
	v_pk_fma_f32 v[0:1], v[0:1], s[10:11], v[64:65] op_sel_hi:[1,0,1]
	v_pk_fma_f32 v[2:3], v[2:3], s[10:11], v[66:67] op_sel_hi:[1,0,1]
	v_pk_fma_f32 v[4:5], v[4:5], s[10:11], v[68:69] op_sel_hi:[1,0,1]
	v_pk_fma_f32 v[6:7], v[6:7], s[10:11], v[70:71] op_sel_hi:[1,0,1]
	v_pk_fma_f32 v[8:9], v[8:9], s[10:11], v[72:73] op_sel_hi:[1,0,1]
	v_pk_fma_f32 v[10:11], v[10:11], s[10:11], v[74:75] op_sel_hi:[1,0,1]
	v_pk_fma_f32 v[12:13], v[12:13], s[10:11], v[76:77] op_sel_hi:[1,0,1]
	v_pk_fma_f32 v[14:15], v[14:15], s[10:11], v[78:79] op_sel_hi:[1,0,1]
	v_pk_fma_f32 v[16:17], v[16:17], s[10:11], v[80:81] op_sel_hi:[1,0,1]
	v_pk_fma_f32 v[18:19], v[18:19], s[10:11], v[82:83] op_sel_hi:[1,0,1]
	v_pk_fma_f32 v[20:21], v[20:21], s[10:11], v[84:85] op_sel_hi:[1,0,1]
	v_pk_fma_f32 v[22:23], v[22:23], s[10:11], v[86:87] op_sel_hi:[1,0,1]
	v_pk_fma_f32 v[24:25], v[24:25], s[10:11], v[88:89] op_sel_hi:[1,0,1]
	v_pk_fma_f32 v[26:27], v[26:27], s[10:11], v[90:91] op_sel_hi:[1,0,1]
	v_pk_fma_f32 v[28:29], v[28:29], s[10:11], v[92:93] op_sel_hi:[1,0,1]
	v_pk_fma_f32 v[30:31], v[30:31], s[10:11], v[94:95] op_sel_hi:[1,0,1]
	v_pk_add_f32 v[64:65], v[0:1], v[2:3]
	v_pk_add_f32 v[66:67], v[4:5], v[6:7]
	v_pk_add_f32 v[68:69], v[8:9], v[10:11]
	v_pk_add_f32 v[70:71], v[12:13], v[14:15]
	v_pk_add_f32 v[72:73], v[16:17], v[18:19]
	v_pk_add_f32 v[74:75], v[20:21], v[22:23]
	v_pk_add_f32 v[76:77], v[24:25], v[26:27]
	v_pk_add_f32 v[78:79], v[28:29], v[30:31]
	v_pk_add_f32 v[80:81], v[64:65], v[66:67]
	v_pk_add_f32 v[82:83], v[68:69], v[70:71]
	v_pk_add_f32 v[84:85], v[72:73], v[74:75]
	v_pk_add_f32 v[86:87], v[76:77], v[78:79]
	v_pk_add_f32 v[64:65], v[80:81], v[82:83]
	v_pk_add_f32 v[66:67], v[84:85], v[86:87]
	s_nop 0
	v_pk_add_f32 v[64:65], v[64:65], v[66:67]
	s_nop 0
	v_add_f32_e32 v96, v64, v65
	ds_bpermute_b32 v97, v109, v96
	s_waitcnt lgkmcnt(0)
	v_add_f32_e32 v96, v96, v97
	ds_bpermute_b32 v97, v110, v96
	s_waitcnt lgkmcnt(0)
	v_add_f32_e32 v96, v96, v97
	ds_bpermute_b32 v97, v111, v96
	s_waitcnt lgkmcnt(0)
	v_add_f32_e32 v96, v96, v97
	ds_bpermute_b32 v97, v240, v96
	s_waitcnt lgkmcnt(0)
	v_add_f32_e32 v96, v96, v97
	ds_bpermute_b32 v97, v241, v96
	s_waitcnt lgkmcnt(0)
	v_add_f32_e32 v96, v96, v97
	ds_bpermute_b32 v97, v242, v96
	s_waitcnt lgkmcnt(0)
	v_add_f32_e32 v96, v96, v97
	v_mul_f32_e32 v96, 0xba000000, v96
	v_pk_add_f32 v[0:1], v[0:1], v[96:97] op_sel_hi:[1,0]
	v_pk_add_f32 v[2:3], v[2:3], v[96:97] op_sel_hi:[1,0]
	v_pk_add_f32 v[4:5], v[4:5], v[96:97] op_sel_hi:[1,0]
	v_pk_add_f32 v[6:7], v[6:7], v[96:97] op_sel_hi:[1,0]
	v_pk_add_f32 v[8:9], v[8:9], v[96:97] op_sel_hi:[1,0]
	v_pk_add_f32 v[10:11], v[10:11], v[96:97] op_sel_hi:[1,0]
	v_pk_add_f32 v[12:13], v[12:13], v[96:97] op_sel_hi:[1,0]
	v_pk_add_f32 v[14:15], v[14:15], v[96:97] op_sel_hi:[1,0]
	v_pk_add_f32 v[16:17], v[16:17], v[96:97] op_sel_hi:[1,0]
	v_pk_add_f32 v[18:19], v[18:19], v[96:97] op_sel_hi:[1,0]
	v_pk_add_f32 v[20:21], v[20:21], v[96:97] op_sel_hi:[1,0]
	v_pk_add_f32 v[22:23], v[22:23], v[96:97] op_sel_hi:[1,0]
	v_pk_add_f32 v[24:25], v[24:25], v[96:97] op_sel_hi:[1,0]
	v_pk_add_f32 v[26:27], v[26:27], v[96:97] op_sel_hi:[1,0]
	v_pk_add_f32 v[28:29], v[28:29], v[96:97] op_sel_hi:[1,0]
	v_pk_add_f32 v[30:31], v[30:31], v[96:97] op_sel_hi:[1,0]
	v_pk_mul_f32 v[64:65], v[0:1], v[0:1]
	v_pk_mul_f32 v[66:67], v[4:5], v[4:5]
	v_pk_mul_f32 v[68:69], v[8:9], v[8:9]
	v_pk_mul_f32 v[70:71], v[12:13], v[12:13]
	v_pk_fma_f32 v[64:65], v[2:3], v[2:3], v[64:65]
	v_pk_fma_f32 v[66:67], v[6:7], v[6:7], v[66:67]
	v_pk_fma_f32 v[68:69], v[10:11], v[10:11], v[68:69]
	v_pk_fma_f32 v[70:71], v[14:15], v[14:15], v[70:71]
	v_pk_fma_f32 v[64:65], v[16:17], v[16:17], v[64:65]
	v_pk_fma_f32 v[66:67], v[20:21], v[20:21], v[66:67]
	v_pk_fma_f32 v[68:69], v[24:25], v[24:25], v[68:69]
	v_pk_fma_f32 v[70:71], v[28:29], v[28:29], v[70:71]
	v_pk_fma_f32 v[64:65], v[18:19], v[18:19], v[64:65]
	v_pk_fma_f32 v[66:67], v[22:23], v[22:23], v[66:67]
	v_pk_fma_f32 v[68:69], v[26:27], v[26:27], v[68:69]
	v_pk_fma_f32 v[70:71], v[30:31], v[30:31], v[70:71]
	v_pk_add_f32 v[64:65], v[64:65], v[66:67]
	v_pk_add_f32 v[68:69], v[68:69], v[70:71]
	s_nop 0
	v_pk_add_f32 v[64:65], v[64:65], v[68:69]
	s_nop 0
	v_add_f32_e32 v96, v64, v65
	ds_bpermute_b32 v97, v109, v96
	s_waitcnt lgkmcnt(0)
	v_add_f32_e32 v96, v96, v97
	ds_bpermute_b32 v97, v110, v96
	s_waitcnt lgkmcnt(0)
	v_add_f32_e32 v96, v96, v97
	ds_bpermute_b32 v97, v111, v96
	s_waitcnt lgkmcnt(0)
	v_add_f32_e32 v96, v96, v97
	ds_bpermute_b32 v97, v240, v96
	s_waitcnt lgkmcnt(0)
; __device__ __forceinline__ unsigned cvtpk(float lo, float hi) { f32x2_t v = {lo, hi}; bf16x2_t b = __builtin_convertvector(v, bf16x2_t); return __builtin_bit_cast(unsigned, b); }
; __global__ void __launch_bounds__(NTHREADS, 2) fwd_megakernel(Args args) {
;     ...
;         const float rstd = 1.f / sqrtf(wave_sum(s2) * (1.f / DM) + LN_EPS);
; #pragma unroll
;         for (int j = 0; j < 8; ++j) { const int c = 4 * (lane + 64 * j); const f32x4 gg = *(const f32x4*)(ln1_g + c), bb = *(const f32x4*)(ln1_b + c);
;             const f32x4 o = v[j] * rstd * gg + bb; *(f32x4*)(row + c) = o;
;             v2u wv; wv.x = cvtpk(o[0], o[1]); wv.y = cvtpk(o[2], o[3]); *(v2u*)(HB + (size_t)m * DM + c) = wv; }
;     ...
;         for (int j = 0; j < 8; ++j) { const int c = 4 * (lane + 64 * j); const f32x4 hv = *(const f32x4*)(row + c); const v2u mv = *(const v2u*)(mr + c);
;             v[j] = hv * ALPHA + (f32x4){bflo(mv.x), bfhi(mv.x), bflo(mv.y), bfhi(mv.y)}; s += (v[j][0] + v[j][1]) + (v[j][2] + v[j][3]); }
;         const float mean = wave_sum(s) * (1.f / DM); float s2 = 0.f;
	v_add_f32_e32 v96, v96, v97
	ds_bpermute_b32 v97, v241, v96
	s_waitcnt lgkmcnt(0)
	v_add_f32_e32 v96, v96, v97
	ds_bpermute_b32 v97, v242, v96
	s_waitcnt lgkmcnt(0)
	v_add_f32_e32 v96, v96, v97
	v_fmamk_f32 v98, v96, 0x3a000000, v105
	v_mul_f32_e32 v99, 0x4f800000, v98
	v_cmp_gt_f32_e32 vcc, s17, v98
	s_nop 1
	v_cndmask_b32_e32 v98, v98, v99, vcc
	v_sqrt_f32_e32 v99, v98
	s_nop 0
	v_add_u32_e32 v100, -1, v99
	v_add_u32_e32 v101, 1, v99
	v_fma_f32 v102, -v100, v99, v98
	v_fma_f32 v103, -v101, v99, v98
	v_cmp_ge_f32_e64 s[0:1], 0, v102
	s_nop 1
	v_cndmask_b32_e64 v99, v99, v100, s[0:1]
	v_cmp_lt_f32_e64 s[0:1], 0, v103
	s_nop 1
	v_cndmask_b32_e64 v99, v99, v101, s[0:1]
	v_mul_f32_e32 v100, 0x37800000, v99
	v_cndmask_b32_e32 v99, v99, v100, vcc
	v_cmp_class_f32_e32 vcc, v98, v104
	s_nop 1
	v_cndmask_b32_e32 v98, v99, v98, vcc
	v_div_scale_f32 v99, s[0:1], v98, v98, 1.0
	v_rcp_f32_e32 v101, v99
	v_div_scale_f32 v100, vcc, 1.0, v98, 1.0
	v_fma_f32 v102, -v99, v101, 1.0
	v_fmac_f32_e32 v101, v102, v101
	v_mul_f32_e32 v102, v100, v101
	v_fma_f32 v103, -v99, v102, v100
	v_fmac_f32_e32 v102, v103, v101
	v_fma_f32 v99, -v99, v102, v100
	v_div_fmas_f32 v99, v99, v101, v102
	v_div_fixup_f32 v98, v99, v98, 1.0
	v_pk_mul_f32 v[0:1], v[98:99], v[0:1] op_sel_hi:[0,1]
	v_pk_mul_f32 v[2:3], v[98:99], v[2:3] op_sel_hi:[0,1]
	v_pk_mul_f32 v[4:5], v[98:99], v[4:5] op_sel_hi:[0,1]
	v_pk_mul_f32 v[6:7], v[98:99], v[6:7] op_sel_hi:[0,1]
	v_pk_mul_f32 v[8:9], v[98:99], v[8:9] op_sel_hi:[0,1]
	v_pk_mul_f32 v[10:11], v[98:99], v[10:11] op_sel_hi:[0,1]
	v_pk_mul_f32 v[12:13], v[98:99], v[12:13] op_sel_hi:[0,1]
	v_pk_mul_f32 v[14:15], v[98:99], v[14:15] op_sel_hi:[0,1]
	v_pk_mul_f32 v[16:17], v[98:99], v[16:17] op_sel_hi:[0,1]
	v_pk_mul_f32 v[18:19], v[98:99], v[18:19] op_sel_hi:[0,1]
	v_pk_mul_f32 v[20:21], v[98:99], v[20:21] op_sel_hi:[0,1]
	v_pk_mul_f32 v[22:23], v[98:99], v[22:23] op_sel_hi:[0,1]
	v_pk_mul_f32 v[24:25], v[98:99], v[24:25] op_sel_hi:[0,1]
	v_pk_mul_f32 v[26:27], v[98:99], v[26:27] op_sel_hi:[0,1]
	v_pk_mul_f32 v[28:29], v[98:99], v[28:29] op_sel_hi:[0,1]
	v_pk_mul_f32 v[30:31], v[98:99], v[30:31] op_sel_hi:[0,1]
	v_pk_fma_f32 v[0:1], v[0:1], v[112:113], v[144:145]
	v_pk_fma_f32 v[2:3], v[2:3], v[114:115], v[146:147]
	v_pk_fma_f32 v[4:5], v[4:5], v[116:117], v[148:149]
	v_pk_fma_f32 v[6:7], v[6:7], v[118:119], v[150:151]
	v_pk_fma_f32 v[8:9], v[8:9], v[120:121], v[152:153]
	v_pk_fma_f32 v[10:11], v[10:11], v[122:123], v[154:155]
	v_pk_fma_f32 v[12:13], v[12:13], v[124:125], v[156:157]
	v_pk_fma_f32 v[14:15], v[14:15], v[126:127], v[158:159]
	v_pk_fma_f32 v[16:17], v[16:17], v[128:129], v[160:161]
	v_pk_fma_f32 v[18:19], v[18:19], v[130:131], v[162:163]
	v_pk_fma_f32 v[20:21], v[20:21], v[132:133], v[164:165]
	v_pk_fma_f32 v[22:23], v[22:23], v[134:135], v[166:167]
	v_pk_fma_f32 v[24:25], v[24:25], v[136:137], v[168:169]
	v_pk_fma_f32 v[26:27], v[26:27], v[138:139], v[170:171]
	v_pk_fma_f32 v[28:29], v[28:29], v[140:141], v[172:173]
	v_pk_fma_f32 v[30:31], v[30:31], v[142:143], v[174:175]
	s_waitcnt vmcnt(8)
	v_lshlrev_b32_e32 v64, 16, v48
	v_and_b32_e32 v65, 0xffff0000, v48
	v_lshlrev_b32_e32 v66, 16, v49
	v_and_b32_e32 v67, 0xffff0000, v49
	v_lshlrev_b32_e32 v68, 16, v50
	v_and_b32_e32 v69, 0xffff0000, v50
	v_lshlrev_b32_e32 v70, 16, v51
	v_and_b32_e32 v71, 0xffff0000, v51
	v_lshlrev_b32_e32 v72, 16, v52
	v_and_b32_e32 v73, 0xffff0000, v52
	v_lshlrev_b32_e32 v74, 16, v53
	v_and_b32_e32 v75, 0xffff0000, v53
	v_lshlrev_b32_e32 v76, 16, v54
	v_and_b32_e32 v77, 0xffff0000, v54
	v_lshlrev_b32_e32 v78, 16, v55
	v_and_b32_e32 v79, 0xffff0000, v55
	v_lshlrev_b32_e32 v80, 16, v56
	v_and_b32_e32 v81, 0xffff0000, v56
	v_lshlrev_b32_e32 v82, 16, v57
	v_and_b32_e32 v83, 0xffff0000, v57
	v_lshlrev_b32_e32 v84, 16, v58
	v_and_b32_e32 v85, 0xffff0000, v58
	v_lshlrev_b32_e32 v86, 16, v59
	v_and_b32_e32 v87, 0xffff0000, v59
	v_lshlrev_b32_e32 v88, 16, v60
	v_and_b32_e32 v89, 0xffff0000, v60
	v_lshlrev_b32_e32 v90, 16, v61
	v_and_b32_e32 v91, 0xffff0000, v61
	v_lshlrev_b32_e32 v92, 16, v62
	v_and_b32_e32 v93, 0xffff0000, v62
	v_lshlrev_b32_e32 v94, 16, v63
	v_and_b32_e32 v95, 0xffff0000, v63
	v_pk_fma_f32 v[0:1], v[0:1], s[10:11], v[64:65] op_sel_hi:[1,0,1]
	v_pk_fma_f32 v[2:3], v[2:3], s[10:11], v[66:67] op_sel_hi:[1,0,1]
	v_pk_fma_f32 v[4:5], v[4:5], s[10:11], v[68:69] op_sel_hi:[1,0,1]
	v_pk_fma_f32 v[6:7], v[6:7], s[10:11], v[70:71] op_sel_hi:[1,0,1]
	v_pk_fma_f32 v[8:9], v[8:9], s[10:11], v[72:73] op_sel_hi:[1,0,1]
	v_pk_fma_f32 v[10:11], v[10:11], s[10:11], v[74:75] op_sel_hi:[1,0,1]
	v_pk_fma_f32 v[12:13], v[12:13], s[10:11], v[76:77] op_sel_hi:[1,0,1]
	v_pk_fma_f32 v[14:15], v[14:15], s[10:11], v[78:79] op_sel_hi:[1,0,1]
	v_pk_fma_f32 v[16:17], v[16:17], s[10:11], v[80:81] op_sel_hi:[1,0,1]
	v_pk_fma_f32 v[18:19], v[18:19], s[10:11], v[82:83] op_sel_hi:[1,0,1]
	v_pk_fma_f32 v[20:21], v[20:21], s[10:11], v[84:85] op_sel_hi:[1,0,1]
	v_pk_fma_f32 v[22:23], v[22:23], s[10:11], v[86:87] op_sel_hi:[1,0,1]
	v_pk_fma_f32 v[24:25], v[24:25], s[10:11], v[88:89] op_sel_hi:[1,0,1]
	v_pk_fma_f32 v[26:27], v[26:27], s[10:11], v[90:91] op_sel_hi:[1,0,1]
	v_pk_fma_f32 v[28:29], v[28:29], s[10:11], v[92:93] op_sel_hi:[1,0,1]
	v_pk_fma_f32 v[30:31], v[30:31], s[10:11], v[94:95] op_sel_hi:[1,0,1]
	v_pk_add_f32 v[64:65], v[0:1], v[2:3]
	v_pk_add_f32 v[66:67], v[4:5], v[6:7]
	v_pk_add_f32 v[68:69], v[8:9], v[10:11]
	v_pk_add_f32 v[70:71], v[12:13], v[14:15]
	v_pk_add_f32 v[72:73], v[16:17], v[18:19]
	v_pk_add_f32 v[74:75], v[20:21], v[22:23]
	v_pk_add_f32 v[76:77], v[24:25], v[26:27]
	v_pk_add_f32 v[78:79], v[28:29], v[30:31]
	v_pk_add_f32 v[80:81], v[64:65], v[66:67]
	v_pk_add_f32 v[82:83], v[68:69], v[70:71]
	v_pk_add_f32 v[84:85], v[72:73], v[74:75]
	v_pk_add_f32 v[86:87], v[76:77], v[78:79]
	v_pk_add_f32 v[64:65], v[80:81], v[82:83]
	v_pk_add_f32 v[66:67], v[84:85], v[86:87]
	s_nop 0
	v_pk_add_f32 v[64:65], v[64:65], v[66:67]
	s_nop 0
	v_add_f32_e32 v96, v64, v65
	ds_bpermute_b32 v97, v109, v96
	s_waitcnt lgkmcnt(0)
; __global__ void __launch_bounds__(NTHREADS, 2) fwd_megakernel(Args args) {
;     ...
;         const float mean = wave_sum(s) * (1.f / DM); float s2 = 0.f;
; #pragma unroll
;         for (int j = 0; j < 8; ++j) { v[j] = v[j] - mean; s2 += (v[j][0] * v[j][0] + v[j][1] * v[j][1]) + (v[j][2] * v[j][2] + v[j][3] * v[j][3]); }
;         const float rstd = 1.f / sqrtf(wave_sum(s2) * (1.f / DM) + LN_EPS);
	v_add_f32_e32 v96, v96, v97
	ds_bpermute_b32 v97, v110, v96
	s_waitcnt lgkmcnt(0)
	v_add_f32_e32 v96, v96, v97
	ds_bpermute_b32 v97, v111, v96
	s_waitcnt lgkmcnt(0)
	v_add_f32_e32 v96, v96, v97
	ds_bpermute_b32 v97, v240, v96
	s_waitcnt lgkmcnt(0)
	v_add_f32_e32 v96, v96, v97
	ds_bpermute_b32 v97, v241, v96
	s_waitcnt lgkmcnt(0)
	v_add_f32_e32 v96, v96, v97
	ds_bpermute_b32 v97, v242, v96
	s_waitcnt lgkmcnt(0)
	v_add_f32_e32 v96, v96, v97
	v_mul_f32_e32 v96, 0xba000000, v96
	v_pk_add_f32 v[0:1], v[0:1], v[96:97] op_sel_hi:[1,0]
	v_pk_add_f32 v[2:3], v[2:3], v[96:97] op_sel_hi:[1,0]
	v_pk_add_f32 v[4:5], v[4:5], v[96:97] op_sel_hi:[1,0]
	v_pk_add_f32 v[6:7], v[6:7], v[96:97] op_sel_hi:[1,0]
	v_pk_add_f32 v[8:9], v[8:9], v[96:97] op_sel_hi:[1,0]
	v_pk_add_f32 v[10:11], v[10:11], v[96:97] op_sel_hi:[1,0]
	v_pk_add_f32 v[12:13], v[12:13], v[96:97] op_sel_hi:[1,0]
	v_pk_add_f32 v[14:15], v[14:15], v[96:97] op_sel_hi:[1,0]
	v_pk_add_f32 v[16:17], v[16:17], v[96:97] op_sel_hi:[1,0]
	v_pk_add_f32 v[18:19], v[18:19], v[96:97] op_sel_hi:[1,0]
	v_pk_add_f32 v[20:21], v[20:21], v[96:97] op_sel_hi:[1,0]
	v_pk_add_f32 v[22:23], v[22:23], v[96:97] op_sel_hi:[1,0]
	v_pk_add_f32 v[24:25], v[24:25], v[96:97] op_sel_hi:[1,0]
	v_pk_add_f32 v[26:27], v[26:27], v[96:97] op_sel_hi:[1,0]
	v_pk_add_f32 v[28:29], v[28:29], v[96:97] op_sel_hi:[1,0]
	v_pk_add_f32 v[30:31], v[30:31], v[96:97] op_sel_hi:[1,0]
	v_pk_mul_f32 v[64:65], v[0:1], v[0:1]
	v_pk_mul_f32 v[66:67], v[4:5], v[4:5]
	v_pk_mul_f32 v[68:69], v[8:9], v[8:9]
	v_pk_mul_f32 v[70:71], v[12:13], v[12:13]
	v_pk_fma_f32 v[64:65], v[2:3], v[2:3], v[64:65]
	v_pk_fma_f32 v[66:67], v[6:7], v[6:7], v[66:67]
	v_pk_fma_f32 v[68:69], v[10:11], v[10:11], v[68:69]
	v_pk_fma_f32 v[70:71], v[14:15], v[14:15], v[70:71]
	v_pk_fma_f32 v[64:65], v[16:17], v[16:17], v[64:65]
	v_pk_fma_f32 v[66:67], v[20:21], v[20:21], v[66:67]
	v_pk_fma_f32 v[68:69], v[24:25], v[24:25], v[68:69]
	v_pk_fma_f32 v[70:71], v[28:29], v[28:29], v[70:71]
	v_pk_fma_f32 v[64:65], v[18:19], v[18:19], v[64:65]
	v_pk_fma_f32 v[66:67], v[22:23], v[22:23], v[66:67]
	v_pk_fma_f32 v[68:69], v[26:27], v[26:27], v[68:69]
	v_pk_fma_f32 v[70:71], v[30:31], v[30:31], v[70:71]
	v_pk_add_f32 v[64:65], v[64:65], v[66:67]
	v_pk_add_f32 v[68:69], v[68:69], v[70:71]
	s_nop 0
	v_pk_add_f32 v[64:65], v[64:65], v[68:69]
	s_nop 0
	v_add_f32_e32 v96, v64, v65
	ds_bpermute_b32 v97, v109, v96
	s_waitcnt lgkmcnt(0)
	v_add_f32_e32 v96, v96, v97
	ds_bpermute_b32 v97, v110, v96
	s_waitcnt lgkmcnt(0)
	v_add_f32_e32 v96, v96, v97
	ds_bpermute_b32 v97, v111, v96
	s_waitcnt lgkmcnt(0)
	v_add_f32_e32 v96, v96, v97
	ds_bpermute_b32 v97, v240, v96
	s_waitcnt lgkmcnt(0)
	v_add_f32_e32 v96, v96, v97
	ds_bpermute_b32 v97, v241, v96
	s_waitcnt lgkmcnt(0)
	v_add_f32_e32 v96, v96, v97
	ds_bpermute_b32 v97, v242, v96
	s_waitcnt lgkmcnt(0)
	v_add_f32_e32 v96, v96, v97
	v_fmamk_f32 v98, v96, 0x3a000000, v105
	v_mul_f32_e32 v99, 0x4f800000, v98
	v_cmp_gt_f32_e32 vcc, s17, v98
	s_nop 1
	v_cndmask_b32_e32 v98, v98, v99, vcc
	v_sqrt_f32_e32 v99, v98
	s_nop 0
	v_add_u32_e32 v100, -1, v99
	v_add_u32_e32 v101, 1, v99
	v_fma_f32 v102, -v100, v99, v98
	v_fma_f32 v103, -v101, v99, v98
	v_cmp_ge_f32_e64 s[0:1], 0, v102
	s_nop 1
	v_cndmask_b32_e64 v99, v99, v100, s[0:1]
	v_cmp_lt_f32_e64 s[0:1], 0, v103
	s_nop 1
	v_cndmask_b32_e64 v99, v99, v101, s[0:1]
	v_mul_f32_e32 v100, 0x37800000, v99
	v_cndmask_b32_e32 v99, v99, v100, vcc
	v_cmp_class_f32_e32 vcc, v98, v104
	s_nop 1
	v_cndmask_b32_e32 v98, v99, v98, vcc
	v_div_scale_f32 v99, s[0:1], v98, v98, 1.0
	v_rcp_f32_e32 v101, v99
	v_div_scale_f32 v100, vcc, 1.0, v98, 1.0
	v_fma_f32 v102, -v99, v101, 1.0
	v_fmac_f32_e32 v101, v102, v101
	v_mul_f32_e32 v102, v100, v101
	v_fma_f32 v103, -v99, v102, v100
	v_fmac_f32_e32 v102, v103, v101
	v_fma_f32 v99, -v99, v102, v100
	v_div_fmas_f32 v99, v99, v101, v102
	v_div_fixup_f32 v98, v99, v98, 1.0
	s_add_i32 s16, s16, s28
	global_load_dwordx4 v[64:67], v106, s[4:5] nt
	global_load_dwordx4 v[68:71], v106, s[4:5] offset:1024 nt
	global_load_dwordx4 v[72:75], v106, s[4:5] offset:2048 nt
	global_load_dwordx4 v[76:79], v106, s[4:5] offset:3072 nt
	global_load_dwordx4 v[80:83], v107, s[4:5] nt
	global_load_dwordx4 v[84:87], v107, s[4:5] offset:1024 nt
	global_load_dwordx4 v[88:91], v107, s[4:5] offset:2048 nt
	global_load_dwordx4 v[92:95], v107, s[4:5] offset:3072 nt
	global_load_dwordx2 v[32:33], v108, s[6:7]
	global_load_dwordx2 v[34:35], v108, s[6:7] offset:512
	global_load_dwordx2 v[36:37], v108, s[6:7] offset:1024
	global_load_dwordx2 v[38:39], v108, s[6:7] offset:1536
	global_load_dwordx2 v[40:41], v108, s[6:7] offset:2048
	global_load_dwordx2 v[42:43], v108, s[6:7] offset:2560
	global_load_dwordx2 v[44:45], v108, s[6:7] offset:3072
	global_load_dwordx2 v[46:47], v108, s[6:7] offset:3584
	global_load_dwordx2 v[48:49], v108, s[8:9]
	global_load_dwordx2 v[50:51], v108, s[8:9] offset:512
	global_load_dwordx2 v[52:53], v108, s[8:9] offset:1024
	global_load_dwordx2 v[54:55], v108, s[8:9] offset:1536
	global_load_dwordx2 v[56:57], v108, s[8:9] offset:2048
	global_load_dwordx2 v[58:59], v108, s[8:9] offset:2560
	global_load_dwordx2 v[60:61], v108, s[8:9] offset:3072
	global_load_dwordx2 v[62:63], v108, s[8:9] offset:3584
	s_add_u32 s4, s4, s12
	s_addc_u32 s5, s5, s13
	s_add_u32 s6, s6, s14
	s_addc_u32 s7, s7, s15
	s_add_u32 s8, s8, s14
	s_addc_u32 s9, s9, s15
	v_pk_mul_f32 v[0:1], v[98:99], v[0:1] op_sel_hi:[0,1]
	v_pk_mul_f32 v[2:3], v[98:99], v[2:3] op_sel_hi:[0,1]
	v_pk_mul_f32 v[4:5], v[98:99], v[4:5] op_sel_hi:[0,1]
	v_pk_mul_f32 v[6:7], v[98:99], v[6:7] op_sel_hi:[0,1]
	v_pk_mul_f32 v[8:9], v[98:99], v[8:9] op_sel_hi:[0,1]
; __global__ void __launch_bounds__(NTHREADS, 2) fwd_megakernel(Args args) {
;     ...
;         float* row = HF + (size_t)m * DM; const float* xr = x + (size_t)m * DM; const bf16* mr = MIXB + (size_t)m * DM; f32x4 v[8]; float s = 0.f;
; #pragma unroll
;         for (int j = 0; j < 8; ++j) { const int c = 4 * (lane + 64 * j); const f32x4 xv = __builtin_nontemporal_load((const f32x4*)(xr + c)); const v2u mv = *(const v2u*)(mr + c);
;             v[j] = xv * ALPHA + (f32x4){bflo(mv.x), bfhi(mv.x), bflo(mv.y), bfhi(mv.y)}; s += (v[j][0] + v[j][1]) + (v[j][2] + v[j][3]); }
;         const float mean = wave_sum(s) * (1.f / DM); float s2 = 0.f;
;     ...
;         const float rstd = 1.f / sqrtf(wave_sum(s2) * (1.f / DM) + LN_EPS);
; #pragma unroll
;         for (int j = 0; j < 8; ++j) { const int c = 4 * (lane + 64 * j); const f32x4 gg = *(const f32x4*)(ln2_g + c), bb = *(const f32x4*)(ln2_b + c);
;             __builtin_nontemporal_store(v[j] * rstd * gg + bb, (f32x4*)(args.out + (size_t)m * DM + c)); }
	v_pk_mul_f32 v[10:11], v[98:99], v[10:11] op_sel_hi:[0,1]
	v_pk_mul_f32 v[12:13], v[98:99], v[12:13] op_sel_hi:[0,1]
	v_pk_mul_f32 v[14:15], v[98:99], v[14:15] op_sel_hi:[0,1]
	v_pk_mul_f32 v[16:17], v[98:99], v[16:17] op_sel_hi:[0,1]
	v_pk_mul_f32 v[18:19], v[98:99], v[18:19] op_sel_hi:[0,1]
	v_pk_mul_f32 v[20:21], v[98:99], v[20:21] op_sel_hi:[0,1]
	v_pk_mul_f32 v[22:23], v[98:99], v[22:23] op_sel_hi:[0,1]
	v_pk_mul_f32 v[24:25], v[98:99], v[24:25] op_sel_hi:[0,1]
	v_pk_mul_f32 v[26:27], v[98:99], v[26:27] op_sel_hi:[0,1]
	v_pk_mul_f32 v[28:29], v[98:99], v[28:29] op_sel_hi:[0,1]
	v_pk_mul_f32 v[30:31], v[98:99], v[30:31] op_sel_hi:[0,1]
	v_pk_fma_f32 v[0:1], v[0:1], v[176:177], v[208:209]
	v_pk_fma_f32 v[2:3], v[2:3], v[178:179], v[210:211]
	global_store_dwordx4 v106, v[0:3], s[2:3] nt
	v_pk_fma_f32 v[4:5], v[4:5], v[180:181], v[212:213]
	v_pk_fma_f32 v[6:7], v[6:7], v[182:183], v[214:215]
	global_store_dwordx4 v106, v[4:7], s[2:3] offset:1024 nt
	v_pk_fma_f32 v[8:9], v[8:9], v[184:185], v[216:217]
	v_pk_fma_f32 v[10:11], v[10:11], v[186:187], v[218:219]
	global_store_dwordx4 v106, v[8:11], s[2:3] offset:2048 nt
	v_pk_fma_f32 v[12:13], v[12:13], v[188:189], v[220:221]
	v_pk_fma_f32 v[14:15], v[14:15], v[190:191], v[222:223]
	global_store_dwordx4 v106, v[12:15], s[2:3] offset:3072 nt
	v_pk_fma_f32 v[16:17], v[16:17], v[192:193], v[224:225]
	v_pk_fma_f32 v[18:19], v[18:19], v[194:195], v[226:227]
	global_store_dwordx4 v107, v[16:19], s[2:3] nt
	v_pk_fma_f32 v[20:21], v[20:21], v[196:197], v[228:229]
	v_pk_fma_f32 v[22:23], v[22:23], v[198:199], v[230:231]
	global_store_dwordx4 v107, v[20:23], s[2:3] offset:1024 nt
	v_pk_fma_f32 v[24:25], v[24:25], v[200:201], v[232:233]
	v_pk_fma_f32 v[26:27], v[26:27], v[202:203], v[234:235]
	global_store_dwordx4 v107, v[24:27], s[2:3] offset:2048 nt
	v_pk_fma_f32 v[28:29], v[28:29], v[204:205], v[236:237]
	v_pk_fma_f32 v[30:31], v[30:31], v[206:207], v[238:239]
	global_store_dwordx4 v107, v[28:31], s[2:3] offset:3072 nt
	s_add_u32 s2, s2, s12
	s_addc_u32 s3, s3, s13
	s_waitcnt vmcnt(16)
	v_lshlrev_b32_e32 v0, 16, v32
	v_and_b32_e32 v1, 0xffff0000, v32
	v_lshlrev_b32_e32 v2, 16, v33
	v_and_b32_e32 v3, 0xffff0000, v33
	v_lshlrev_b32_e32 v4, 16, v34
	v_and_b32_e32 v5, 0xffff0000, v34
	v_lshlrev_b32_e32 v6, 16, v35
	v_and_b32_e32 v7, 0xffff0000, v35
	v_lshlrev_b32_e32 v8, 16, v36
	v_and_b32_e32 v9, 0xffff0000, v36
	v_lshlrev_b32_e32 v10, 16, v37
	v_and_b32_e32 v11, 0xffff0000, v37
	v_lshlrev_b32_e32 v12, 16, v38
	v_and_b32_e32 v13, 0xffff0000, v38
	v_lshlrev_b32_e32 v14, 16, v39
	v_and_b32_e32 v15, 0xffff0000, v39
	v_lshlrev_b32_e32 v16, 16, v40
	v_and_b32_e32 v17, 0xffff0000, v40
	v_lshlrev_b32_e32 v18, 16, v41
	v_and_b32_e32 v19, 0xffff0000, v41
	v_lshlrev_b32_e32 v20, 16, v42
	v_and_b32_e32 v21, 0xffff0000, v42
	v_lshlrev_b32_e32 v22, 16, v43
	v_and_b32_e32 v23, 0xffff0000, v43
	v_lshlrev_b32_e32 v24, 16, v44
	v_and_b32_e32 v25, 0xffff0000, v44
	v_lshlrev_b32_e32 v26, 16, v45
	v_and_b32_e32 v27, 0xffff0000, v45
	v_lshlrev_b32_e32 v28, 16, v46
	v_and_b32_e32 v29, 0xffff0000, v46
	v_lshlrev_b32_e32 v30, 16, v47
	v_and_b32_e32 v31, 0xffff0000, v47
	v_pk_fma_f32 v[64:65], v[64:65], s[10:11], v[0:1] op_sel_hi:[1,0,1]
	v_pk_fma_f32 v[66:67], v[66:67], s[10:11], v[2:3] op_sel_hi:[1,0,1]
	v_pk_fma_f32 v[68:69], v[68:69], s[10:11], v[4:5] op_sel_hi:[1,0,1]
	v_pk_fma_f32 v[70:71], v[70:71], s[10:11], v[6:7] op_sel_hi:[1,0,1]
	v_pk_fma_f32 v[72:73], v[72:73], s[10:11], v[8:9] op_sel_hi:[1,0,1]
	v_pk_fma_f32 v[74:75], v[74:75], s[10:11], v[10:11] op_sel_hi:[1,0,1]
	v_pk_fma_f32 v[76:77], v[76:77], s[10:11], v[12:13] op_sel_hi:[1,0,1]
	v_pk_fma_f32 v[78:79], v[78:79], s[10:11], v[14:15] op_sel_hi:[1,0,1]
	v_pk_fma_f32 v[80:81], v[80:81], s[10:11], v[16:17] op_sel_hi:[1,0,1]
	v_pk_fma_f32 v[82:83], v[82:83], s[10:11], v[18:19] op_sel_hi:[1,0,1]
	v_pk_fma_f32 v[84:85], v[84:85], s[10:11], v[20:21] op_sel_hi:[1,0,1]
	v_pk_fma_f32 v[86:87], v[86:87], s[10:11], v[22:23] op_sel_hi:[1,0,1]
	v_pk_fma_f32 v[88:89], v[88:89], s[10:11], v[24:25] op_sel_hi:[1,0,1]
	v_pk_fma_f32 v[90:91], v[90:91], s[10:11], v[26:27] op_sel_hi:[1,0,1]
	v_pk_fma_f32 v[92:93], v[92:93], s[10:11], v[28:29] op_sel_hi:[1,0,1]
	v_pk_fma_f32 v[94:95], v[94:95], s[10:11], v[30:31] op_sel_hi:[1,0,1]
	v_pk_add_f32 v[0:1], v[64:65], v[66:67]
	v_pk_add_f32 v[2:3], v[68:69], v[70:71]
	v_pk_add_f32 v[4:5], v[72:73], v[74:75]
	v_pk_add_f32 v[6:7], v[76:77], v[78:79]
	v_pk_add_f32 v[8:9], v[80:81], v[82:83]
	v_pk_add_f32 v[10:11], v[84:85], v[86:87]
	v_pk_add_f32 v[12:13], v[88:89], v[90:91]
	v_pk_add_f32 v[14:15], v[92:93], v[94:95]
	v_pk_add_f32 v[16:17], v[0:1], v[2:3]
	v_pk_add_f32 v[18:19], v[4:5], v[6:7]
	v_pk_add_f32 v[20:21], v[8:9], v[10:11]
	v_pk_add_f32 v[22:23], v[12:13], v[14:15]
	v_pk_add_f32 v[0:1], v[16:17], v[18:19]
	v_pk_add_f32 v[2:3], v[20:21], v[22:23]
	s_nop 0
	v_pk_add_f32 v[0:1], v[0:1], v[2:3]
	s_nop 0
	v_add_f32_e32 v96, v0, v1
	ds_bpermute_b32 v97, v109, v96
	s_waitcnt lgkmcnt(0)
	v_add_f32_e32 v96, v96, v97
	ds_bpermute_b32 v97, v110, v96
	s_waitcnt lgkmcnt(0)
	v_add_f32_e32 v96, v96, v97
	ds_bpermute_b32 v97, v111, v96
	s_waitcnt lgkmcnt(0)
	v_add_f32_e32 v96, v96, v97
	ds_bpermute_b32 v97, v240, v96
	s_waitcnt lgkmcnt(0)
	v_add_f32_e32 v96, v96, v97
	ds_bpermute_b32 v97, v241, v96
	s_waitcnt lgkmcnt(0)
	v_add_f32_e32 v96, v96, v97
	ds_bpermute_b32 v97, v242, v96
	s_waitcnt lgkmcnt(0)
; __global__ void __launch_bounds__(NTHREADS, 2) fwd_megakernel(Args args) {
;     ...
;         const float mean = wave_sum(s) * (1.f / DM); float s2 = 0.f;
; #pragma unroll
;         for (int j = 0; j < 8; ++j) { v[j] = v[j] - mean; s2 += (v[j][0] * v[j][0] + v[j][1] * v[j][1]) + (v[j][2] * v[j][2] + v[j][3] * v[j][3]); }
;         const float rstd = 1.f / sqrtf(wave_sum(s2) * (1.f / DM) + LN_EPS);
; #pragma unroll
;         for (int j = 0; j < 8; ++j) { const int c = 4 * (lane + 64 * j); const f32x4 gg = *(const f32x4*)(ln1_g + c), bb = *(const f32x4*)(ln1_b + c);
;             const f32x4 o = v[j] * rstd * gg + bb; *(f32x4*)(row + c) = o;
	v_add_f32_e32 v96, v96, v97
	v_mul_f32_e32 v96, 0xba000000, v96
	v_pk_add_f32 v[64:65], v[64:65], v[96:97] op_sel_hi:[1,0]
	v_pk_add_f32 v[66:67], v[66:67], v[96:97] op_sel_hi:[1,0]
	v_pk_add_f32 v[68:69], v[68:69], v[96:97] op_sel_hi:[1,0]
	v_pk_add_f32 v[70:71], v[70:71], v[96:97] op_sel_hi:[1,0]
	v_pk_add_f32 v[72:73], v[72:73], v[96:97] op_sel_hi:[1,0]
	v_pk_add_f32 v[74:75], v[74:75], v[96:97] op_sel_hi:[1,0]
	v_pk_add_f32 v[76:77], v[76:77], v[96:97] op_sel_hi:[1,0]
	v_pk_add_f32 v[78:79], v[78:79], v[96:97] op_sel_hi:[1,0]
	v_pk_add_f32 v[80:81], v[80:81], v[96:97] op_sel_hi:[1,0]
	v_pk_add_f32 v[82:83], v[82:83], v[96:97] op_sel_hi:[1,0]
	v_pk_add_f32 v[84:85], v[84:85], v[96:97] op_sel_hi:[1,0]
	v_pk_add_f32 v[86:87], v[86:87], v[96:97] op_sel_hi:[1,0]
	v_pk_add_f32 v[88:89], v[88:89], v[96:97] op_sel_hi:[1,0]
	v_pk_add_f32 v[90:91], v[90:91], v[96:97] op_sel_hi:[1,0]
	v_pk_add_f32 v[92:93], v[92:93], v[96:97] op_sel_hi:[1,0]
	v_pk_add_f32 v[94:95], v[94:95], v[96:97] op_sel_hi:[1,0]
	v_pk_mul_f32 v[0:1], v[64:65], v[64:65]
	v_pk_mul_f32 v[2:3], v[68:69], v[68:69]
	v_pk_mul_f32 v[4:5], v[72:73], v[72:73]
	v_pk_mul_f32 v[6:7], v[76:77], v[76:77]
	v_pk_fma_f32 v[0:1], v[66:67], v[66:67], v[0:1]
	v_pk_fma_f32 v[2:3], v[70:71], v[70:71], v[2:3]
	v_pk_fma_f32 v[4:5], v[74:75], v[74:75], v[4:5]
	v_pk_fma_f32 v[6:7], v[78:79], v[78:79], v[6:7]
	v_pk_fma_f32 v[0:1], v[80:81], v[80:81], v[0:1]
	v_pk_fma_f32 v[2:3], v[84:85], v[84:85], v[2:3]
	v_pk_fma_f32 v[4:5], v[88:89], v[88:89], v[4:5]
	v_pk_fma_f32 v[6:7], v[92:93], v[92:93], v[6:7]
	v_pk_fma_f32 v[0:1], v[82:83], v[82:83], v[0:1]
	v_pk_fma_f32 v[2:3], v[86:87], v[86:87], v[2:3]
	v_pk_fma_f32 v[4:5], v[90:91], v[90:91], v[4:5]
	v_pk_fma_f32 v[6:7], v[94:95], v[94:95], v[6:7]
	v_pk_add_f32 v[0:1], v[0:1], v[2:3]
	v_pk_add_f32 v[4:5], v[4:5], v[6:7]
	s_nop 0
	v_pk_add_f32 v[0:1], v[0:1], v[4:5]
	s_nop 0
	v_add_f32_e32 v96, v0, v1
	ds_bpermute_b32 v97, v109, v96
	s_waitcnt lgkmcnt(0)
	v_add_f32_e32 v96, v96, v97
	ds_bpermute_b32 v97, v110, v96
	s_waitcnt lgkmcnt(0)
	v_add_f32_e32 v96, v96, v97
	ds_bpermute_b32 v97, v111, v96
	s_waitcnt lgkmcnt(0)
	v_add_f32_e32 v96, v96, v97
	ds_bpermute_b32 v97, v240, v96
	s_waitcnt lgkmcnt(0)
	v_add_f32_e32 v96, v96, v97
	ds_bpermute_b32 v97, v241, v96
	s_waitcnt lgkmcnt(0)
	v_add_f32_e32 v96, v96, v97
	ds_bpermute_b32 v97, v242, v96
	s_waitcnt lgkmcnt(0)
	v_add_f32_e32 v96, v96, v97
	v_fmamk_f32 v98, v96, 0x3a000000, v105
	v_mul_f32_e32 v99, 0x4f800000, v98
	v_cmp_gt_f32_e32 vcc, s17, v98
	s_nop 1
	v_cndmask_b32_e32 v98, v98, v99, vcc
	v_sqrt_f32_e32 v99, v98
	s_nop 0
	v_add_u32_e32 v100, -1, v99
	v_add_u32_e32 v101, 1, v99
	v_fma_f32 v102, -v100, v99, v98
	v_fma_f32 v103, -v101, v99, v98
	v_cmp_ge_f32_e64 s[0:1], 0, v102
	s_nop 1
	v_cndmask_b32_e64 v99, v99, v100, s[0:1]
	v_cmp_lt_f32_e64 s[0:1], 0, v103
	s_nop 1
	v_cndmask_b32_e64 v99, v99, v101, s[0:1]
	v_mul_f32_e32 v100, 0x37800000, v99
	v_cndmask_b32_e32 v99, v99, v100, vcc
	v_cmp_class_f32_e32 vcc, v98, v104
	s_nop 1
	v_cndmask_b32_e32 v98, v99, v98, vcc
	v_div_scale_f32 v99, s[0:1], v98, v98, 1.0
	v_rcp_f32_e32 v101, v99
	v_div_scale_f32 v100, vcc, 1.0, v98, 1.0
	v_fma_f32 v102, -v99, v101, 1.0
	v_fmac_f32_e32 v101, v102, v101
	v_mul_f32_e32 v102, v100, v101
	v_fma_f32 v103, -v99, v102, v100
	v_fmac_f32_e32 v102, v103, v101
	v_fma_f32 v99, -v99, v102, v100
	v_div_fmas_f32 v99, v99, v101, v102
	v_div_fixup_f32 v98, v99, v98, 1.0
	v_pk_mul_f32 v[64:65], v[98:99], v[64:65] op_sel_hi:[0,1]
	v_pk_mul_f32 v[66:67], v[98:99], v[66:67] op_sel_hi:[0,1]
	v_pk_mul_f32 v[68:69], v[98:99], v[68:69] op_sel_hi:[0,1]
	v_pk_mul_f32 v[70:71], v[98:99], v[70:71] op_sel_hi:[0,1]
	v_pk_mul_f32 v[72:73], v[98:99], v[72:73] op_sel_hi:[0,1]
	v_pk_mul_f32 v[74:75], v[98:99], v[74:75] op_sel_hi:[0,1]
	v_pk_mul_f32 v[76:77], v[98:99], v[76:77] op_sel_hi:[0,1]
	v_pk_mul_f32 v[78:79], v[98:99], v[78:79] op_sel_hi:[0,1]
	v_pk_mul_f32 v[80:81], v[98:99], v[80:81] op_sel_hi:[0,1]
	v_pk_mul_f32 v[82:83], v[98:99], v[82:83] op_sel_hi:[0,1]
	v_pk_mul_f32 v[84:85], v[98:99], v[84:85] op_sel_hi:[0,1]
	v_pk_mul_f32 v[86:87], v[98:99], v[86:87] op_sel_hi:[0,1]
	v_pk_mul_f32 v[88:89], v[98:99], v[88:89] op_sel_hi:[0,1]
	v_pk_mul_f32 v[90:91], v[98:99], v[90:91] op_sel_hi:[0,1]
	v_pk_mul_f32 v[92:93], v[98:99], v[92:93] op_sel_hi:[0,1]
	v_pk_mul_f32 v[94:95], v[98:99], v[94:95] op_sel_hi:[0,1]
	v_pk_fma_f32 v[64:65], v[64:65], v[112:113], v[144:145]
	v_pk_fma_f32 v[66:67], v[66:67], v[114:115], v[146:147]
	v_pk_fma_f32 v[68:69], v[68:69], v[116:117], v[148:149]
	v_pk_fma_f32 v[70:71], v[70:71], v[118:119], v[150:151]
	v_pk_fma_f32 v[72:73], v[72:73], v[120:121], v[152:153]
	v_pk_fma_f32 v[74:75], v[74:75], v[122:123], v[154:155]
	v_pk_fma_f32 v[76:77], v[76:77], v[124:125], v[156:157]
	v_pk_fma_f32 v[78:79], v[78:79], v[126:127], v[158:159]
	v_pk_fma_f32 v[80:81], v[80:81], v[128:129], v[160:161]
	v_pk_fma_f32 v[82:83], v[82:83], v[130:131], v[162:163]
	v_pk_fma_f32 v[84:85], v[84:85], v[132:133], v[164:165]
	v_pk_fma_f32 v[86:87], v[86:87], v[134:135], v[166:167]
	v_pk_fma_f32 v[88:89], v[88:89], v[136:137], v[168:169]
	v_pk_fma_f32 v[90:91], v[90:91], v[138:139], v[170:171]
	v_pk_fma_f32 v[92:93], v[92:93], v[140:141], v[172:173]
	v_pk_fma_f32 v[94:95], v[94:95], v[142:143], v[174:175]
	s_waitcnt vmcnt(8)
; __global__ void __launch_bounds__(NTHREADS, 2) fwd_megakernel(Args args) {
;     ...
;         for (int j = 0; j < 8; ++j) { const int c = 4 * (lane + 64 * j); const f32x4 hv = *(const f32x4*)(row + c); const v2u mv = *(const v2u*)(mr + c);
;             v[j] = hv * ALPHA + (f32x4){bflo(mv.x), bfhi(mv.x), bflo(mv.y), bfhi(mv.y)}; s += (v[j][0] + v[j][1]) + (v[j][2] + v[j][3]); }
;         const float mean = wave_sum(s) * (1.f / DM); float s2 = 0.f;
; #pragma unroll
;         for (int j = 0; j < 8; ++j) { v[j] = v[j] - mean; s2 += (v[j][0] * v[j][0] + v[j][1] * v[j][1]) + (v[j][2] * v[j][2] + v[j][3] * v[j][3]); }
;         const float rstd = 1.f / sqrtf(wave_sum(s2) * (1.f / DM) + LN_EPS);
	v_lshlrev_b32_e32 v0, 16, v48
	v_and_b32_e32 v1, 0xffff0000, v48
	v_lshlrev_b32_e32 v2, 16, v49
	v_and_b32_e32 v3, 0xffff0000, v49
	v_lshlrev_b32_e32 v4, 16, v50
	v_and_b32_e32 v5, 0xffff0000, v50
	v_lshlrev_b32_e32 v6, 16, v51
	v_and_b32_e32 v7, 0xffff0000, v51
	v_lshlrev_b32_e32 v8, 16, v52
	v_and_b32_e32 v9, 0xffff0000, v52
	v_lshlrev_b32_e32 v10, 16, v53
	v_and_b32_e32 v11, 0xffff0000, v53
	v_lshlrev_b32_e32 v12, 16, v54
	v_and_b32_e32 v13, 0xffff0000, v54
	v_lshlrev_b32_e32 v14, 16, v55
	v_and_b32_e32 v15, 0xffff0000, v55
	v_lshlrev_b32_e32 v16, 16, v56
	v_and_b32_e32 v17, 0xffff0000, v56
	v_lshlrev_b32_e32 v18, 16, v57
	v_and_b32_e32 v19, 0xffff0000, v57
	v_lshlrev_b32_e32 v20, 16, v58
	v_and_b32_e32 v21, 0xffff0000, v58
	v_lshlrev_b32_e32 v22, 16, v59
	v_and_b32_e32 v23, 0xffff0000, v59
	v_lshlrev_b32_e32 v24, 16, v60
	v_and_b32_e32 v25, 0xffff0000, v60
	v_lshlrev_b32_e32 v26, 16, v61
	v_and_b32_e32 v27, 0xffff0000, v61
	v_lshlrev_b32_e32 v28, 16, v62
	v_and_b32_e32 v29, 0xffff0000, v62
	v_lshlrev_b32_e32 v30, 16, v63
	v_and_b32_e32 v31, 0xffff0000, v63
	v_pk_fma_f32 v[64:65], v[64:65], s[10:11], v[0:1] op_sel_hi:[1,0,1]
	v_pk_fma_f32 v[66:67], v[66:67], s[10:11], v[2:3] op_sel_hi:[1,0,1]
	v_pk_fma_f32 v[68:69], v[68:69], s[10:11], v[4:5] op_sel_hi:[1,0,1]
	v_pk_fma_f32 v[70:71], v[70:71], s[10:11], v[6:7] op_sel_hi:[1,0,1]
	v_pk_fma_f32 v[72:73], v[72:73], s[10:11], v[8:9] op_sel_hi:[1,0,1]
	v_pk_fma_f32 v[74:75], v[74:75], s[10:11], v[10:11] op_sel_hi:[1,0,1]
	v_pk_fma_f32 v[76:77], v[76:77], s[10:11], v[12:13] op_sel_hi:[1,0,1]
	v_pk_fma_f32 v[78:79], v[78:79], s[10:11], v[14:15] op_sel_hi:[1,0,1]
	v_pk_fma_f32 v[80:81], v[80:81], s[10:11], v[16:17] op_sel_hi:[1,0,1]
	v_pk_fma_f32 v[82:83], v[82:83], s[10:11], v[18:19] op_sel_hi:[1,0,1]
	v_pk_fma_f32 v[84:85], v[84:85], s[10:11], v[20:21] op_sel_hi:[1,0,1]
	v_pk_fma_f32 v[86:87], v[86:87], s[10:11], v[22:23] op_sel_hi:[1,0,1]
	v_pk_fma_f32 v[88:89], v[88:89], s[10:11], v[24:25] op_sel_hi:[1,0,1]
	v_pk_fma_f32 v[90:91], v[90:91], s[10:11], v[26:27] op_sel_hi:[1,0,1]
	v_pk_fma_f32 v[92:93], v[92:93], s[10:11], v[28:29] op_sel_hi:[1,0,1]
	v_pk_fma_f32 v[94:95], v[94:95], s[10:11], v[30:31] op_sel_hi:[1,0,1]
	v_pk_add_f32 v[0:1], v[64:65], v[66:67]
	v_pk_add_f32 v[2:3], v[68:69], v[70:71]
	v_pk_add_f32 v[4:5], v[72:73], v[74:75]
	v_pk_add_f32 v[6:7], v[76:77], v[78:79]
	v_pk_add_f32 v[8:9], v[80:81], v[82:83]
	v_pk_add_f32 v[10:11], v[84:85], v[86:87]
	v_pk_add_f32 v[12:13], v[88:89], v[90:91]
	v_pk_add_f32 v[14:15], v[92:93], v[94:95]
	v_pk_add_f32 v[16:17], v[0:1], v[2:3]
	v_pk_add_f32 v[18:19], v[4:5], v[6:7]
	v_pk_add_f32 v[20:21], v[8:9], v[10:11]
	v_pk_add_f32 v[22:23], v[12:13], v[14:15]
	v_pk_add_f32 v[0:1], v[16:17], v[18:19]
	v_pk_add_f32 v[2:3], v[20:21], v[22:23]
	s_nop 0
	v_pk_add_f32 v[0:1], v[0:1], v[2:3]
	s_nop 0
	v_add_f32_e32 v96, v0, v1
	ds_bpermute_b32 v97, v109, v96
	s_waitcnt lgkmcnt(0)
	v_add_f32_e32 v96, v96, v97
	ds_bpermute_b32 v97, v110, v96
	s_waitcnt lgkmcnt(0)
	v_add_f32_e32 v96, v96, v97
	ds_bpermute_b32 v97, v111, v96
	s_waitcnt lgkmcnt(0)
	v_add_f32_e32 v96, v96, v97
	ds_bpermute_b32 v97, v240, v96
	s_waitcnt lgkmcnt(0)
	v_add_f32_e32 v96, v96, v97
	ds_bpermute_b32 v97, v241, v96
	s_waitcnt lgkmcnt(0)
	v_add_f32_e32 v96, v96, v97
	ds_bpermute_b32 v97, v242, v96
	s_waitcnt lgkmcnt(0)
	v_add_f32_e32 v96, v96, v97
	v_mul_f32_e32 v96, 0xba000000, v96
	v_pk_add_f32 v[64:65], v[64:65], v[96:97] op_sel_hi:[1,0]
	v_pk_add_f32 v[66:67], v[66:67], v[96:97] op_sel_hi:[1,0]
	v_pk_add_f32 v[68:69], v[68:69], v[96:97] op_sel_hi:[1,0]
	v_pk_add_f32 v[70:71], v[70:71], v[96:97] op_sel_hi:[1,0]
	v_pk_add_f32 v[72:73], v[72:73], v[96:97] op_sel_hi:[1,0]
	v_pk_add_f32 v[74:75], v[74:75], v[96:97] op_sel_hi:[1,0]
	v_pk_add_f32 v[76:77], v[76:77], v[96:97] op_sel_hi:[1,0]
	v_pk_add_f32 v[78:79], v[78:79], v[96:97] op_sel_hi:[1,0]
	v_pk_add_f32 v[80:81], v[80:81], v[96:97] op_sel_hi:[1,0]
	v_pk_add_f32 v[82:83], v[82:83], v[96:97] op_sel_hi:[1,0]
	v_pk_add_f32 v[84:85], v[84:85], v[96:97] op_sel_hi:[1,0]
	v_pk_add_f32 v[86:87], v[86:87], v[96:97] op_sel_hi:[1,0]
	v_pk_add_f32 v[88:89], v[88:89], v[96:97] op_sel_hi:[1,0]
	v_pk_add_f32 v[90:91], v[90:91], v[96:97] op_sel_hi:[1,0]
	v_pk_add_f32 v[92:93], v[92:93], v[96:97] op_sel_hi:[1,0]
	v_pk_add_f32 v[94:95], v[94:95], v[96:97] op_sel_hi:[1,0]
	v_pk_mul_f32 v[0:1], v[64:65], v[64:65]
	v_pk_mul_f32 v[2:3], v[68:69], v[68:69]
	v_pk_mul_f32 v[4:5], v[72:73], v[72:73]
	v_pk_mul_f32 v[6:7], v[76:77], v[76:77]
	v_pk_fma_f32 v[0:1], v[66:67], v[66:67], v[0:1]
	v_pk_fma_f32 v[2:3], v[70:71], v[70:71], v[2:3]
	v_pk_fma_f32 v[4:5], v[74:75], v[74:75], v[4:5]
	v_pk_fma_f32 v[6:7], v[78:79], v[78:79], v[6:7]
	v_pk_fma_f32 v[0:1], v[80:81], v[80:81], v[0:1]
	v_pk_fma_f32 v[2:3], v[84:85], v[84:85], v[2:3]
	v_pk_fma_f32 v[4:5], v[88:89], v[88:89], v[4:5]
	v_pk_fma_f32 v[6:7], v[92:93], v[92:93], v[6:7]
	v_pk_fma_f32 v[0:1], v[82:83], v[82:83], v[0:1]
	v_pk_fma_f32 v[2:3], v[86:87], v[86:87], v[2:3]
	v_pk_fma_f32 v[4:5], v[90:91], v[90:91], v[4:5]
	v_pk_fma_f32 v[6:7], v[94:95], v[94:95], v[6:7]
	v_pk_add_f32 v[0:1], v[0:1], v[2:3]
	v_pk_add_f32 v[4:5], v[4:5], v[6:7]
	s_nop 0
	v_pk_add_f32 v[0:1], v[0:1], v[4:5]
	s_nop 0
	v_add_f32_e32 v96, v0, v1
	ds_bpermute_b32 v97, v109, v96
	s_waitcnt lgkmcnt(0)
	v_add_f32_e32 v96, v96, v97
	ds_bpermute_b32 v97, v110, v96
	s_waitcnt lgkmcnt(0)
	v_add_f32_e32 v96, v96, v97
	ds_bpermute_b32 v97, v111, v96
	s_waitcnt lgkmcnt(0)
	v_add_f32_e32 v96, v96, v97
	ds_bpermute_b32 v97, v240, v96
	s_waitcnt lgkmcnt(0)
	v_add_f32_e32 v96, v96, v97
	ds_bpermute_b32 v97, v241, v96
	s_waitcnt lgkmcnt(0)
	v_add_f32_e32 v96, v96, v97
	ds_bpermute_b32 v97, v242, v96
	s_waitcnt lgkmcnt(0)
	v_add_f32_e32 v96, v96, v97
	v_fmamk_f32 v98, v96, 0x3a000000, v105
	v_mul_f32_e32 v99, 0x4f800000, v98
	v_cmp_gt_f32_e32 vcc, s17, v98
	s_nop 1
	v_cndmask_b32_e32 v98, v98, v99, vcc
	v_sqrt_f32_e32 v99, v98
	s_nop 0
	v_add_u32_e32 v100, -1, v99
	v_add_u32_e32 v101, 1, v99
	v_fma_f32 v102, -v100, v99, v98
	v_fma_f32 v103, -v101, v99, v98
	v_cmp_ge_f32_e64 s[0:1], 0, v102
	s_nop 1
	v_cndmask_b32_e64 v99, v99, v100, s[0:1]
	v_cmp_lt_f32_e64 s[0:1], 0, v103
	s_nop 1
	v_cndmask_b32_e64 v99, v99, v101, s[0:1]
	v_mul_f32_e32 v100, 0x37800000, v99
	v_cndmask_b32_e32 v99, v99, v100, vcc
	v_cmp_class_f32_e32 vcc, v98, v104
	s_nop 1
	v_cndmask_b32_e32 v98, v99, v98, vcc
	v_div_scale_f32 v99, s[0:1], v98, v98, 1.0
	v_rcp_f32_e32 v101, v99
	v_div_scale_f32 v100, vcc, 1.0, v98, 1.0
	v_fma_f32 v102, -v99, v101, 1.0
	v_fmac_f32_e32 v101, v102, v101
	v_mul_f32_e32 v102, v100, v101
	v_fma_f32 v103, -v99, v102, v100
	v_fmac_f32_e32 v102, v103, v101
	v_fma_f32 v99, -v99, v102, v100
	v_div_fmas_f32 v99, v99, v101, v102
	v_div_fixup_f32 v98, v99, v98, 1.0
	s_add_i32 s16, s16, s28
	s_cmp_lt_i32 s16, 0x8000
	s_cbranch_scc0 .Lp9r_last
; __global__ void __launch_bounds__(NTHREADS, 2) fwd_megakernel(Args args) {
;     ...
;         const float rstd = 1.f / sqrtf(wave_sum(s2) * (1.f / DM) + LN_EPS);
; #pragma unroll
;         for (int j = 0; j < 8; ++j) { const int c = 4 * (lane + 64 * j); const f32x4 gg = *(const f32x4*)(ln2_g + c), bb = *(const f32x4*)(ln2_b + c);
;             __builtin_nontemporal_store(v[j] * rstd * gg + bb, (f32x4*)(args.out + (size_t)m * DM + c)); }
	global_load_dwordx4 v[0:3], v106, s[4:5] nt
	global_load_dwordx4 v[4:7], v106, s[4:5] offset:1024 nt
	global_load_dwordx4 v[8:11], v106, s[4:5] offset:2048 nt
	global_load_dwordx4 v[12:15], v106, s[4:5] offset:3072 nt
	global_load_dwordx4 v[16:19], v107, s[4:5] nt
	global_load_dwordx4 v[20:23], v107, s[4:5] offset:1024 nt
	global_load_dwordx4 v[24:27], v107, s[4:5] offset:2048 nt
	global_load_dwordx4 v[28:31], v107, s[4:5] offset:3072 nt
	global_load_dwordx2 v[32:33], v108, s[6:7]
	global_load_dwordx2 v[34:35], v108, s[6:7] offset:512
	global_load_dwordx2 v[36:37], v108, s[6:7] offset:1024
	global_load_dwordx2 v[38:39], v108, s[6:7] offset:1536
	global_load_dwordx2 v[40:41], v108, s[6:7] offset:2048
	global_load_dwordx2 v[42:43], v108, s[6:7] offset:2560
	global_load_dwordx2 v[44:45], v108, s[6:7] offset:3072
	global_load_dwordx2 v[46:47], v108, s[6:7] offset:3584
	global_load_dwordx2 v[48:49], v108, s[8:9]
	global_load_dwordx2 v[50:51], v108, s[8:9] offset:512
	global_load_dwordx2 v[52:53], v108, s[8:9] offset:1024
	global_load_dwordx2 v[54:55], v108, s[8:9] offset:1536
	global_load_dwordx2 v[56:57], v108, s[8:9] offset:2048
	global_load_dwordx2 v[58:59], v108, s[8:9] offset:2560
	global_load_dwordx2 v[60:61], v108, s[8:9] offset:3072
	global_load_dwordx2 v[62:63], v108, s[8:9] offset:3584
	s_add_u32 s4, s4, s12
	s_addc_u32 s5, s5, s13
	s_add_u32 s6, s6, s14
	s_addc_u32 s7, s7, s15
	s_add_u32 s8, s8, s14
	s_addc_u32 s9, s9, s15
.Lp9r_last:
	v_pk_mul_f32 v[64:65], v[98:99], v[64:65] op_sel_hi:[0,1]
	v_pk_mul_f32 v[66:67], v[98:99], v[66:67] op_sel_hi:[0,1]
	v_pk_mul_f32 v[68:69], v[98:99], v[68:69] op_sel_hi:[0,1]
	v_pk_mul_f32 v[70:71], v[98:99], v[70:71] op_sel_hi:[0,1]
	v_pk_mul_f32 v[72:73], v[98:99], v[72:73] op_sel_hi:[0,1]
	v_pk_mul_f32 v[74:75], v[98:99], v[74:75] op_sel_hi:[0,1]
	v_pk_mul_f32 v[76:77], v[98:99], v[76:77] op_sel_hi:[0,1]
	v_pk_mul_f32 v[78:79], v[98:99], v[78:79] op_sel_hi:[0,1]
	v_pk_mul_f32 v[80:81], v[98:99], v[80:81] op_sel_hi:[0,1]
	v_pk_mul_f32 v[82:83], v[98:99], v[82:83] op_sel_hi:[0,1]
	v_pk_mul_f32 v[84:85], v[98:99], v[84:85] op_sel_hi:[0,1]
	v_pk_mul_f32 v[86:87], v[98:99], v[86:87] op_sel_hi:[0,1]
	v_pk_mul_f32 v[88:89], v[98:99], v[88:89] op_sel_hi:[0,1]
	v_pk_mul_f32 v[90:91], v[98:99], v[90:91] op_sel_hi:[0,1]
	v_pk_mul_f32 v[92:93], v[98:99], v[92:93] op_sel_hi:[0,1]
	v_pk_mul_f32 v[94:95], v[98:99], v[94:95] op_sel_hi:[0,1]
	v_pk_fma_f32 v[64:65], v[64:65], v[176:177], v[208:209]
	v_pk_fma_f32 v[66:67], v[66:67], v[178:179], v[210:211]
	global_store_dwordx4 v106, v[64:67], s[2:3] nt
	v_pk_fma_f32 v[68:69], v[68:69], v[180:181], v[212:213]
	v_pk_fma_f32 v[70:71], v[70:71], v[182:183], v[214:215]
	global_store_dwordx4 v106, v[68:71], s[2:3] offset:1024 nt
	v_pk_fma_f32 v[72:73], v[72:73], v[184:185], v[216:217]
	v_pk_fma_f32 v[74:75], v[74:75], v[186:187], v[218:219]
	global_store_dwordx4 v106, v[72:75], s[2:3] offset:2048 nt
	v_pk_fma_f32 v[76:77], v[76:77], v[188:189], v[220:221]
	v_pk_fma_f32 v[78:79], v[78:79], v[190:191], v[222:223]
	global_store_dwordx4 v106, v[76:79], s[2:3] offset:3072 nt
	v_pk_fma_f32 v[80:81], v[80:81], v[192:193], v[224:225]
	v_pk_fma_f32 v[82:83], v[82:83], v[194:195], v[226:227]
	global_store_dwordx4 v107, v[80:83], s[2:3] nt
	v_pk_fma_f32 v[84:85], v[84:85], v[196:197], v[228:229]
	v_pk_fma_f32 v[86:87], v[86:87], v[198:199], v[230:231]
	global_store_dwordx4 v107, v[84:87], s[2:3] offset:1024 nt
	v_pk_fma_f32 v[88:89], v[88:89], v[200:201], v[232:233]
	v_pk_fma_f32 v[90:91], v[90:91], v[202:203], v[234:235]
	global_store_dwordx4 v107, v[88:91], s[2:3] offset:2048 nt
	v_pk_fma_f32 v[92:93], v[92:93], v[204:205], v[236:237]
	v_pk_fma_f32 v[94:95], v[94:95], v[206:207], v[238:239]
	global_store_dwordx4 v107, v[92:95], s[2:3] offset:3072 nt
	s_add_u32 s2, s2, s12
	s_addc_u32 s3, s3, s13
	s_cmp_lt_i32 s16, 0x8000
	s_cbranch_scc1 .Lp9r_loop
